# v113 + P3's GEMM workgroups (bx<64: inputs from P0 only) arrive at seam 2 but do not wait for the rest of the XCD
# speedup vs baseline: 1.0054x; 1.0042x over previous
; __device__ __forceinline__ unsigned xb_ld(unsigned* p)              { return __hip_atomic_load(p, __ATOMIC_RELAXED, __HIP_MEMORY_SCOPE_AGENT); }
; __device__ __forceinline__ unsigned xb_add(unsigned* p, unsigned v) { return __hip_atomic_fetch_add(p, v, __ATOMIC_RELAXED, __HIP_MEMORY_SCOPE_AGENT); }
; #define XB_SPIN(cond, bar) do { unsigned _sp = 0; while (cond) { __builtin_amdgcn_s_sleep(1); \
;     if ((++_sp & 255u) == 0u) { if (xb_ld(&(bar)[XB_TMO])) break; if (_sp > XB_SPIN_CAP) { atomicAdd(&(bar)[XB_TMO], 1u); break; } } } } while (0)
; #define PH(k) (IN(k) && ((MK_MASK >> (k)) & 1))
; #define REPS(k) for (int rep_ = 0; rep_ < (((MK_REP_MASK) >> (k)) & 1) + 1; ++rep_)
; #define SEAM(k) do { if (IN(k) && IN((k) + 1)) { xcd_barrier(bar, wave == 0 && mk_lane() == 0); } } while (0)
; __device__ __forceinline__ void xcd_barrier(const XcdBarrier& b, bool leader) {
;     asm volatile("s_waitcnt vmcnt(0)" ::: "memory");
;     __syncthreads();
;     if (leader) {
;         unsigned* bar = b.bar;
;         __builtin_amdgcn_s_waitcnt(0);
;         unsigned nloc = b.st[0], nx = b.st[1];
;         if (nloc == 0u) { xcd_barrier_complete(bar, b.x, nloc, nx); b.st[0] = nloc; b.st[1] = nx; }
;         const unsigned old = xb_add(&bar[XB_XSUB(b.x)], 1u);
;         const unsigned gen = old / nloc;
;         if (old + 1u == (gen + 1u) * nloc) {
;             __builtin_amdgcn_fence(__ATOMIC_RELEASE, "agent");
;             asm volatile("s_waitcnt vmcnt(0)" ::: "memory");
;             const unsigned og = xb_add(&bar[XB_TOP], 1u);
;             const unsigned tg = og / nx;
;             if (og + 1u == (tg + 1u) * nx) xb_add(&bar[XB_TOPGEN], 1u);
;             else XB_SPIN(xb_ld(&bar[XB_TOPGEN]) == tg, bar);
;             __builtin_amdgcn_fence(__ATOMIC_ACQUIRE, "agent");
;             xb_add(&bar[XB_XGEN(b.x)], 1u);
;             asm volatile("s_waitcnt vmcnt(0)" ::: "memory");
;         } else {
;             XB_SPIN(xb_ld(&bar[XB_XGEN(b.x)]) == gen, bar);
;             __builtin_amdgcn_fence(__ATOMIC_ACQUIRE, "agent");
;             asm volatile("s_waitcnt vmcnt(0)" ::: "memory");
;         }
;     }
;     __syncthreads();
; }
; __global__ void __launch_bounds__(NWAVES * 64, 2) mk_fwd(Params P) {
;     ...
;         }
;     }
;     SEAM(2);
;     if (PH(3)) REPS(3) {
;         LANE_TID;
;         if (bx < 64) {
.LBB0_750:
	s_waitcnt vmcnt(0)
	s_waitcnt lgkmcnt(0)
	s_barrier
	s_and_saveexec_b64 s[4:5], s[6:7]
	s_cbranch_execz .LBB0_798
	v_readlane_b32 s8, v254, 2
	v_readlane_b32 s9, v254, 3
	s_and_b32 s2, s88, 7
	s_lshl_b32 s2, s2, 8
	s_add_u32 s2, s8, s2
	s_addc_u32 s3, s9, 0
	v_mov_b32_e32 v0, 0
	v_mov_b32_e32 v1, 1
	v_mov_b32_e32 v5, 0x1400
	global_load_dwordx4 v[6:9], v0, s[8:9] offset:768 sc1
	global_load_dwordx4 v[10:13], v0, s[8:9] offset:784 sc1
	global_atomic_add v3, v5, v1, s[2:3] offset:128 sc0
	s_waitcnt vmcnt(0)
	v_add_u32_e32 v14, -1, v6
	v_and_b32_e32 v2, v14, v6
	v_add_u32_e32 v14, -1, v7
	v_and_or_b32 v2, v14, v7, v2
	v_add_u32_e32 v14, -1, v8
	v_and_or_b32 v2, v14, v8, v2
	v_add_u32_e32 v14, -1, v9
	v_and_or_b32 v2, v14, v9, v2
	v_add_u32_e32 v14, -1, v10
	v_and_or_b32 v2, v14, v10, v2
	v_add_u32_e32 v14, -1, v11
	v_and_or_b32 v2, v14, v11, v2
	v_add_u32_e32 v14, -1, v12
	v_and_or_b32 v2, v14, v12, v2
	v_add_u32_e32 v14, -1, v13
	v_and_or_b32 v2, v14, v13, v2
	v_cmp_ne_u32_e32 vcc, 0, v2
	s_cbranch_vccnz .Lmy_glob_k2
	s_cmp_lt_u32 s88, 64
	s_cbranch_scc1 .Lmy_done_k2
	v_and_b32_e32 v4, 0xffffffe0, v3
	v_add_u32_e32 v4, 32, v4
	v_add_u32_e32 v3, 1, v3
	v_cmp_eq_u32_e32 vcc, v3, v4
	s_cbranch_vccnz .Lmy_done_k2
	s_mov_b32 s10, 0
